# sel/MoBA attention far tiles: the tile-constant bias folded into the row maximum and exponent offset instead of 32 per-element adds
# speedup vs baseline: 1.0077x; 1.0077x over previous
; #define MFMA32(a, b, c) __builtin_amdgcn_mfma_f32_32x32x16_bf16((a), (b), (c), 0, 0, 0)
; template <class KP, class VP, class ACT, class FILL>
; DI void attn_loop(AttnSt& st, const bf16x8 (&qf)[4], int k0, int k1, size_t vstride, KP kp, VP vp, ACT act, FILL fill) {
;     ...
;   for (int kt = k0; kt <= k1; ++kt) {
;     const int kn = (kt < k1) ? kt + 1 : k1;
;     const int kn2 = (kt + 2 <= k1) ? kt + 2 : k1;
;     {
;       const bf16_t* v0 = vp(kn);
; #pragma unroll
;       for (int j = 0; j < 8; ++j) nxt.v[j] = *(const s16x4*)(v0 + 256 * j);
;     }
;     bf16x8 k2[4];
;     {
;       const bf16_t* krow = kp(kn2);
; #pragma unroll
;       for (int ss = 0; ss < 4; ++ss) k2[ss] = *(const bf16x8*)(krow + 512 * ss);
;     }
;     f32x16 s_next;
; #pragma unroll
;     for (int i = 0; i < 16; ++i) s_next[i] = 0.f;
; #pragma unroll
;     for (int ss = 0; ss < 4; ++ss) s_next = MFMA32(nxt.k[ss], qf[ss], s_next);
; DI void nsa_main_item(const Params& p, int b, int head, int qb, const unsigned char* blut, const float* tbl) {
;     ...
;     attn_loop(st, qf, 0, qb, 32,
;       [&](int kt) { return K + (size_t)kt * 2048 + (h * 32 + r) * 8; },
;       [&](int kt) { return Vt + (size_t)kt * 2048 + (h * 32 + r) * 4; },
;       [&](int kt) { return __ballot((selm >> (kt >> 1)) & 1ull) != 0ull; },
;       [&](int kt, const f32x16& s, float (&lg)[16]) {
;         const bool bs = (selm >> (kt >> 1)) & 1ull;
.Lasel_loop:
	s_waitcnt vmcnt(2)
	s_barrier
	s_lshr_b32 s23, s56, 1
	s_add_u32 s23, s23, 2
	s_sub_u32 s61, s100, 0x4000
	s_cmp_lt_u32 s61, 0x10000
	s_cselect_b32 s61, 0x18000, s61
	s_lshr_b32 s24, s59, 1
	s_min_u32 s24, s23, s24
	s_lshl_b32 s26, s24, 13
	s_lshl_b32 s24, s58, 10
	s_add_u32 s26, s26, s24
	s_mov_b32 s27, 0
	v_lshl_add_u64 v[248:249], v[148:149], 0, s[26:27]
	v_lshl_add_u64 v[250:251], v[170:171], 0, s[26:27]
	v_add_co_u32_e32 v250, vcc, v250, v247
	v_addc_co_u32_e32 v251, vcc, 0, v251, vcc
	s_add_u32 s24, s24, s61
	s_mov_b32 m0, s24
	s_nop 0
	global_load_lds_dwordx4 v[248:249], off
	s_add_u32 s24, s24, 0x2000
	s_mov_b32 m0, s24
	s_nop 0
	global_load_lds_dwordx4 v[250:251], off
	s_cmp_le_u32 s56, s60
	s_cbranch_scc0 .Lasel_skip
	v_lshl_add_u32 v248, v247, 1, s100
	ds_read_b128 v[96:99], v248 offset:0
	ds_read_b128 v[112:115], v248 offset:4096
	ds_read_b128 v[100:103], v248 offset:1024
	ds_read_b128 v[116:119], v248 offset:5120
	ds_read_b128 v[104:107], v248 offset:2048
	ds_read_b128 v[120:123], v248 offset:6144
	ds_read_b128 v[108:111], v248 offset:3072
	ds_read_b128 v[124:127], v248 offset:7168
	s_sub_i32 s61, s60, s56
	s_lshr_b32 s23, s56, 1
	v_lshrrev_b64 v[248:249], s23, v[168:169]
	v_and_b32_e32 v248, 1, v248
	v_cmp_eq_u32_e64 s[62:63], 1, v248
	s_waitcnt lgkmcnt(6)
	v_mfma_f32_32x32x16_bf16 v[32:47], v[96:99], v[80:83], 0
	v_mfma_f32_32x32x16_bf16 v[48:63], v[112:115], v[80:83], 0
	s_waitcnt lgkmcnt(4)
	v_mfma_f32_32x32x16_bf16 v[32:47], v[100:103], v[84:87], v[32:47]
	v_mfma_f32_32x32x16_bf16 v[48:63], v[116:119], v[84:87], v[48:63]
	s_waitcnt lgkmcnt(2)
	v_mfma_f32_32x32x16_bf16 v[32:47], v[104:107], v[88:91], v[32:47]
	v_mfma_f32_32x32x16_bf16 v[48:63], v[120:123], v[88:91], v[48:63]
	s_waitcnt lgkmcnt(0)
	v_mfma_f32_32x32x16_bf16 v[32:47], v[108:111], v[92:95], v[32:47]
	v_mfma_f32_32x32x16_bf16 v[48:63], v[124:127], v[92:95], v[48:63]
	v_add_u32_e32 v250, s100, v247
	ds_read_b64 v[64:65], v250 offset:8192
	ds_read_b64 v[66:67], v250 offset:8704
	ds_read_b64 v[68:69], v250 offset:9216
	ds_read_b64 v[70:71], v250 offset:9728
	ds_read_b64 v[72:73], v250 offset:10240
	ds_read_b64 v[74:75], v250 offset:10752
	ds_read_b64 v[76:77], v250 offset:11264
	ds_read_b64 v[78:79], v250 offset:11776
	ds_read_b64 v[172:173], v250 offset:12288
	ds_read_b64 v[174:175], v250 offset:12800
	ds_read_b64 v[176:177], v250 offset:13312
	ds_read_b64 v[178:179], v250 offset:13824
	ds_read_b64 v[180:181], v250 offset:14336
	ds_read_b64 v[182:183], v250 offset:14848
	ds_read_b64 v[184:185], v250 offset:15360
	ds_read_b64 v[186:187], v250 offset:15872
	s_cmp_ge_i32 s61, 50
	s_cbranch_scc1 .Lasel_far
; #define NEGINF (-__builtin_inff())
; DI int crow(int i, int h) { return (i & 3) + 8 * (i >> 2) + 4 * h; }
; DI void nsa_main_item(const Params& p, int b, int head, int qb, const unsigned char* blut, const float* tbl) {
;     ...
;           int dist[16]; float bv[16];
; #pragma unroll
;           for (int i = 0; i < 16; ++i) dist[i] = t - (kt * 32 + crow(i, h));
;           bias16(blut, tblh, dist, bv);
; #pragma unroll
;           for (int i = 0; i < 16; ++i) lg[i] = (bs && dist[i] >= 0) ? s[i] + bv[i] : NEGINF;
	s_lshl_b32 s23, s61, 5
	v_add_u32_e32 v241, s23, v221
	v_lshl_add_u32 v244, v241, 2, v242
	v_subrev_u32_e32 v245, 128, v244
	ds_read_b32 v224, v244 offset:108
	ds_read_b32 v225, v244 offset:104
	ds_read_b32 v226, v244 offset:100
	ds_read_b32 v227, v244 offset:96
	ds_read_b32 v228, v244 offset:76
	ds_read_b32 v229, v244 offset:72
	ds_read_b32 v230, v244 offset:68
	ds_read_b32 v231, v244 offset:64
	ds_read_b32 v232, v244 offset:44
	ds_read_b32 v233, v244 offset:40
	ds_read_b32 v234, v244 offset:36
	ds_read_b32 v235, v244 offset:32
	ds_read_b32 v236, v244 offset:12
	ds_read_b32 v237, v244 offset:8
	ds_read_b32 v238, v244 offset:4
	ds_read_b32 v239, v244 offset:0
	s_waitcnt lgkmcnt(8)
	v_add_f32_e32 v32, v32, v224
	v_add_f32_e32 v33, v33, v225
	v_add_f32_e32 v34, v34, v226
	v_add_f32_e32 v35, v35, v227
	v_add_f32_e32 v36, v36, v228
	v_add_f32_e32 v37, v37, v229
	v_add_f32_e32 v38, v38, v230
	v_add_f32_e32 v39, v39, v231
	s_waitcnt lgkmcnt(0)
	v_add_f32_e32 v40, v40, v232
	v_add_f32_e32 v41, v41, v233
	v_add_f32_e32 v42, v42, v234
	v_add_f32_e32 v43, v43, v235
	v_add_f32_e32 v44, v44, v236
	v_add_f32_e32 v45, v45, v237
	v_add_f32_e32 v46, v46, v238
	v_add_f32_e32 v47, v47, v239
	ds_read_b32 v224, v245 offset:108
	ds_read_b32 v225, v245 offset:104
	ds_read_b32 v226, v245 offset:100
	ds_read_b32 v227, v245 offset:96
	ds_read_b32 v228, v245 offset:76
	ds_read_b32 v229, v245 offset:72
	ds_read_b32 v230, v245 offset:68
	ds_read_b32 v231, v245 offset:64
	ds_read_b32 v232, v245 offset:44
	ds_read_b32 v233, v245 offset:40
	ds_read_b32 v234, v245 offset:36
	ds_read_b32 v235, v245 offset:32
	ds_read_b32 v236, v245 offset:12
	ds_read_b32 v237, v245 offset:8
	ds_read_b32 v238, v245 offset:4
	ds_read_b32 v239, v245 offset:0
	s_waitcnt lgkmcnt(8)
	v_add_f32_e32 v48, v48, v224
	v_add_f32_e32 v49, v49, v225
	v_add_f32_e32 v50, v50, v226
	v_add_f32_e32 v51, v51, v227
	v_add_f32_e32 v52, v52, v228
	v_add_f32_e32 v53, v53, v229
	v_add_f32_e32 v54, v54, v230
	v_add_f32_e32 v55, v55, v231
	s_waitcnt lgkmcnt(0)
	v_add_f32_e32 v56, v56, v232
	v_add_f32_e32 v57, v57, v233
	v_add_f32_e32 v58, v58, v234
	v_add_f32_e32 v59, v59, v235
	v_add_f32_e32 v60, v60, v236
	v_add_f32_e32 v61, v61, v237
	v_add_f32_e32 v62, v62, v238
	v_add_f32_e32 v63, v63, v239
	s_cmp_ge_i32 s61, 2
	s_cbranch_scc1 .Lasel_sm0
	v_subrev_u32_e32 v246, 32, v241
	v_cmp_le_i32_e32 vcc, 0, v241
	s_nop 1
	v_cndmask_b32_e32 v32, v199, v32, vcc
	v_cmp_le_i32_e32 vcc, 1, v241
	s_nop 1
	v_cndmask_b32_e32 v33, v199, v33, vcc
	v_cmp_le_i32_e32 vcc, 2, v241
	s_nop 1
	v_cndmask_b32_e32 v34, v199, v34, vcc
	v_cmp_le_i32_e32 vcc, 3, v241
	s_nop 1
	v_cndmask_b32_e32 v35, v199, v35, vcc
	v_cmp_le_i32_e32 vcc, 8, v241
	s_nop 1
	v_cndmask_b32_e32 v36, v199, v36, vcc
	v_cmp_le_i32_e32 vcc, 9, v241
	s_nop 1
	v_cndmask_b32_e32 v37, v199, v37, vcc
	v_cmp_le_i32_e32 vcc, 10, v241
	s_nop 1
	v_cndmask_b32_e32 v38, v199, v38, vcc
	v_cmp_le_i32_e32 vcc, 11, v241
	s_nop 1
	v_cndmask_b32_e32 v39, v199, v39, vcc
	v_cmp_le_i32_e32 vcc, 16, v241
	s_nop 1
	v_cndmask_b32_e32 v40, v199, v40, vcc
	v_cmp_le_i32_e32 vcc, 17, v241
	s_nop 1
	v_cndmask_b32_e32 v41, v199, v41, vcc
	v_cmp_le_i32_e32 vcc, 18, v241
	s_nop 1
	v_cndmask_b32_e32 v42, v199, v42, vcc
	v_cmp_le_i32_e32 vcc, 19, v241
	s_nop 1
	v_cndmask_b32_e32 v43, v199, v43, vcc
	v_cmp_le_i32_e32 vcc, 24, v241
	s_nop 1
	v_cndmask_b32_e32 v44, v199, v44, vcc
	v_cmp_le_i32_e32 vcc, 25, v241
	s_nop 1
	v_cndmask_b32_e32 v45, v199, v45, vcc
	v_cmp_le_i32_e32 vcc, 26, v241
	s_nop 1
	v_cndmask_b32_e32 v46, v199, v46, vcc
	v_cmp_le_i32_e32 vcc, 27, v241
	s_nop 1
	v_cndmask_b32_e32 v47, v199, v47, vcc
	v_cmp_le_i32_e32 vcc, 0, v246
	s_nop 1
	v_cndmask_b32_e32 v48, v199, v48, vcc
	v_cmp_le_i32_e32 vcc, 1, v246
	s_nop 1
	v_cndmask_b32_e32 v49, v199, v49, vcc
	v_cmp_le_i32_e32 vcc, 2, v246
	s_nop 1
	v_cndmask_b32_e32 v50, v199, v50, vcc
	v_cmp_le_i32_e32 vcc, 3, v246
	s_nop 1
	v_cndmask_b32_e32 v51, v199, v51, vcc
	v_cmp_le_i32_e32 vcc, 8, v246
	s_nop 1
	v_cndmask_b32_e32 v52, v199, v52, vcc
	v_cmp_le_i32_e32 vcc, 9, v246
	s_nop 1
	v_cndmask_b32_e32 v53, v199, v53, vcc
	v_cmp_le_i32_e32 vcc, 10, v246
	s_nop 1
	v_cndmask_b32_e32 v54, v199, v54, vcc
	v_cmp_le_i32_e32 vcc, 11, v246
	s_nop 1
	v_cndmask_b32_e32 v55, v199, v55, vcc
	v_cmp_le_i32_e32 vcc, 16, v246
	s_nop 1
	v_cndmask_b32_e32 v56, v199, v56, vcc
	v_cmp_le_i32_e32 vcc, 17, v246
	s_nop 1
	v_cndmask_b32_e32 v57, v199, v57, vcc
	v_cmp_le_i32_e32 vcc, 18, v246
	s_nop 1
	v_cndmask_b32_e32 v58, v199, v58, vcc
	v_cmp_le_i32_e32 vcc, 19, v246
	s_nop 1
	v_cndmask_b32_e32 v59, v199, v59, vcc
	v_cmp_le_i32_e32 vcc, 24, v246
	s_nop 1
	v_cndmask_b32_e32 v60, v199, v60, vcc
	v_cmp_le_i32_e32 vcc, 25, v246
	s_nop 1
	v_cndmask_b32_e32 v61, v199, v61, vcc
	v_cmp_le_i32_e32 vcc, 26, v246
	s_nop 1
	v_cndmask_b32_e32 v62, v199, v62, vcc
	v_cmp_le_i32_e32 vcc, 27, v246
	s_nop 1
	v_cndmask_b32_e32 v63, v199, v63, vcc

; #define MFMA32(a, b, c) __builtin_amdgcn_mfma_f32_32x32x16_bf16((a), (b), (c), 0, 0, 0)
; #define NEGINF (-__builtin_inff())
; DI int crow(int i, int h) { return (i & 3) + 8 * (i >> 2) + 4 * h; }
; template <class KP, class VP, class ACT, class FILL>
; DI void attn_loop(AttnSt& st, const bf16x8 (&qf)[4], int k0, int k1, size_t vstride, KP kp, VP vp, ACT act, FILL fill) {
;     ...
;   for (int kt = k0; kt <= k1; ++kt) {
;     const int kn = (kt < k1) ? kt + 1 : k1;
;     const int kn2 = (kt + 2 <= k1) ? kt + 2 : k1;
;     {
;       const bf16_t* v0 = vp(kn);
; #pragma unroll
;       for (int j = 0; j < 8; ++j) nxt.v[j] = *(const s16x4*)(v0 + 256 * j);
;     }
;     bf16x8 k2[4];
;     {
;       const bf16_t* krow = kp(kn2);
; #pragma unroll
;       for (int ss = 0; ss < 4; ++ss) k2[ss] = *(const bf16x8*)(krow + 512 * ss);
;     }
;     f32x16 s_next;
; #pragma unroll
;     for (int i = 0; i < 16; ++i) s_next[i] = 0.f;
; #pragma unroll
;     for (int ss = 0; ss < 4; ++ss) s_next = MFMA32(nxt.k[ss], qf[ss], s_next);
; DI void moba_item(const Params& p, int b, int hd, int qb, const unsigned char* blut, const float* tbl) {
;     ...
;   attn_loop(st, qf, 0, qb, 32,
;     [&](int kt) { return K + (size_t)kt * 2048 + (h * 32 + r) * 8; },
;     [&](int kt) { return Vt + (size_t)kt * 2048 + (h * 32 + r) * 4; },
;     [&](int kt) { return __ballot((mmask >> (kt >> 3)) & 1u) != 0ull; },
;     [&](int kt, const f32x16& s, float (&lg)[16]) {
;       const bool bs = (mmask >> (kt >> 3)) & 1u;
;       if (qb * 32 - (kt * 32 + 31) >= 1513) {
;         const float b31 = tblh[31];
; #pragma unroll
;         for (int i = 0; i < 16; ++i) lg[i] = bs ? s[i] + b31 : NEGINF;
;       } else {
;         int dist[16]; float bv[16];
; #pragma unroll
;         for (int i = 0; i < 16; ++i) dist[i] = t - (kt * 32 + crow(i, h));
;         bias16(blut, tblh, dist, bv);
; #pragma unroll
;         for (int i = 0; i < 16; ++i) lg[i] = (bs && dist[i] >= 0) ? s[i] + bv[i] : NEGINF;
.Lamoba_loop:
	s_waitcnt vmcnt(2)
	s_barrier
	s_lshr_b32 s23, s56, 1
	s_add_u32 s23, s23, 2
	s_sub_u32 s61, s100, 0x4000
	s_cmp_lt_u32 s61, 0x10000
	s_cselect_b32 s61, 0x18000, s61
	s_lshr_b32 s24, s59, 1
	s_min_u32 s24, s23, s24
	s_lshl_b32 s26, s24, 13
	s_lshl_b32 s24, s58, 10
	s_add_u32 s26, s26, s24
	s_mov_b32 s27, 0
	v_lshl_add_u64 v[186:187], v[134:135], 0, s[26:27]
	v_lshl_add_u64 v[218:219], v[136:137], 0, s[26:27]
	v_add_co_u32_e32 v218, vcc, v218, v185
	v_addc_co_u32_e32 v219, vcc, 0, v219, vcc
	s_add_u32 s24, s24, s61
	s_mov_b32 m0, s24
	s_nop 0
	global_load_lds_dwordx4 v[186:187], off
	s_add_u32 s24, s24, 0x2000
	s_mov_b32 m0, s24
	s_nop 0
	global_load_lds_dwordx4 v[218:219], off
	s_cmp_le_u32 s56, s60
	s_cbranch_scc0 .Lamoba_skip
	v_lshl_add_u32 v186, v185, 1, s100
	ds_read_b128 v[96:99], v186 offset:0
	ds_read_b128 v[112:115], v186 offset:4096
	ds_read_b128 v[100:103], v186 offset:1024
	ds_read_b128 v[116:119], v186 offset:5120
	ds_read_b128 v[104:107], v186 offset:2048
	ds_read_b128 v[120:123], v186 offset:6144
	ds_read_b128 v[108:111], v186 offset:3072
	ds_read_b128 v[124:127], v186 offset:7168
	s_sub_i32 s61, s60, s56
	s_lshr_b32 s23, s56, 3
	v_bfe_u32 v184, v157, s23, 1
	v_cmp_eq_u32_e64 s[62:63], 1, v184
	s_waitcnt lgkmcnt(6)
	v_mfma_f32_32x32x16_bf16 v[32:47], v[96:99], v[80:83], 0
	v_mfma_f32_32x32x16_bf16 v[48:63], v[112:115], v[80:83], 0
	s_waitcnt lgkmcnt(4)
	v_mfma_f32_32x32x16_bf16 v[32:47], v[100:103], v[84:87], v[32:47]
	v_mfma_f32_32x32x16_bf16 v[48:63], v[116:119], v[84:87], v[48:63]
	s_waitcnt lgkmcnt(2)
	v_mfma_f32_32x32x16_bf16 v[32:47], v[104:107], v[88:91], v[32:47]
	v_mfma_f32_32x32x16_bf16 v[48:63], v[120:123], v[88:91], v[48:63]
	s_waitcnt lgkmcnt(0)
	v_mfma_f32_32x32x16_bf16 v[32:47], v[108:111], v[92:95], v[32:47]
	v_mfma_f32_32x32x16_bf16 v[48:63], v[124:127], v[92:95], v[48:63]
	v_add_u32_e32 v218, s100, v185
	ds_read_b64 v[64:65], v218 offset:8192
	ds_read_b64 v[66:67], v218 offset:8704
	ds_read_b64 v[68:69], v218 offset:9216
	ds_read_b64 v[70:71], v218 offset:9728
	ds_read_b64 v[72:73], v218 offset:10240
	ds_read_b64 v[74:75], v218 offset:10752
	ds_read_b64 v[76:77], v218 offset:11264
	ds_read_b64 v[78:79], v218 offset:11776
	ds_read_b64 v[138:139], v218 offset:12288
	ds_read_b64 v[140:141], v218 offset:12800
	ds_read_b64 v[142:143], v218 offset:13312
	ds_read_b64 v[144:145], v218 offset:13824
	ds_read_b64 v[146:147], v218 offset:14336
	ds_read_b64 v[148:149], v218 offset:14848
	ds_read_b64 v[150:151], v218 offset:15360
	ds_read_b64 v[152:153], v218 offset:15872
	s_cmp_ge_i32 s61, 50
	s_cbranch_scc1 .Lamoba_far
; #define NEGINF (-__builtin_inff())
; DI int crow(int i, int h) { return (i & 3) + 8 * (i >> 2) + 4 * h; }
; DI void moba_item(const Params& p, int b, int hd, int qb, const unsigned char* blut, const float* tbl) {
;     ...
;         int dist[16]; float bv[16];
; #pragma unroll
;         for (int i = 0; i < 16; ++i) dist[i] = t - (kt * 32 + crow(i, h));
;         bias16(blut, tblh, dist, bv);
; #pragma unroll
;         for (int i = 0; i < 16; ++i) lg[i] = (bs && dist[i] >= 0) ? s[i] + bv[i] : NEGINF;
	s_lshl_b32 s23, s61, 5
	v_add_u32_e32 v179, s23, v158
	v_lshl_add_u32 v182, v179, 2, v180
	v_subrev_u32_e32 v183, 128, v182
	ds_read_b32 v162, v182 offset:108
	ds_read_b32 v163, v182 offset:104
	ds_read_b32 v164, v182 offset:100
	ds_read_b32 v165, v182 offset:96
	ds_read_b32 v166, v182 offset:76
	ds_read_b32 v167, v182 offset:72
	ds_read_b32 v168, v182 offset:68
	ds_read_b32 v169, v182 offset:64
	ds_read_b32 v170, v182 offset:44
	ds_read_b32 v171, v182 offset:40
	ds_read_b32 v172, v182 offset:36
	ds_read_b32 v173, v182 offset:32
	ds_read_b32 v174, v182 offset:12
	ds_read_b32 v175, v182 offset:8
	ds_read_b32 v176, v182 offset:4
	ds_read_b32 v177, v182 offset:0
	s_waitcnt lgkmcnt(8)
	v_add_f32_e32 v32, v32, v162
	v_add_f32_e32 v33, v33, v163
	v_add_f32_e32 v34, v34, v164
	v_add_f32_e32 v35, v35, v165
	v_add_f32_e32 v36, v36, v166
	v_add_f32_e32 v37, v37, v167
	v_add_f32_e32 v38, v38, v168
	v_add_f32_e32 v39, v39, v169
	s_waitcnt lgkmcnt(0)
	v_add_f32_e32 v40, v40, v170
	v_add_f32_e32 v41, v41, v171
	v_add_f32_e32 v42, v42, v172
	v_add_f32_e32 v43, v43, v173
	v_add_f32_e32 v44, v44, v174
	v_add_f32_e32 v45, v45, v175
	v_add_f32_e32 v46, v46, v176
	v_add_f32_e32 v47, v47, v177
	ds_read_b32 v162, v183 offset:108
	ds_read_b32 v163, v183 offset:104
	ds_read_b32 v164, v183 offset:100
	ds_read_b32 v165, v183 offset:96
	ds_read_b32 v166, v183 offset:76
	ds_read_b32 v167, v183 offset:72
	ds_read_b32 v168, v183 offset:68
	ds_read_b32 v169, v183 offset:64
	ds_read_b32 v170, v183 offset:44
	ds_read_b32 v171, v183 offset:40
	ds_read_b32 v172, v183 offset:36
	ds_read_b32 v173, v183 offset:32
	ds_read_b32 v174, v183 offset:12
	ds_read_b32 v175, v183 offset:8
	ds_read_b32 v176, v183 offset:4
	ds_read_b32 v177, v183 offset:0
	s_waitcnt lgkmcnt(8)
	v_add_f32_e32 v48, v48, v162
	v_add_f32_e32 v49, v49, v163
	v_add_f32_e32 v50, v50, v164
	v_add_f32_e32 v51, v51, v165
	v_add_f32_e32 v52, v52, v166
	v_add_f32_e32 v53, v53, v167
	v_add_f32_e32 v54, v54, v168
	v_add_f32_e32 v55, v55, v169
	s_waitcnt lgkmcnt(0)
	v_add_f32_e32 v56, v56, v170
	v_add_f32_e32 v57, v57, v171
	v_add_f32_e32 v58, v58, v172
	v_add_f32_e32 v59, v59, v173
	v_add_f32_e32 v60, v60, v174
	v_add_f32_e32 v61, v61, v175
	v_add_f32_e32 v62, v62, v176
	v_add_f32_e32 v63, v63, v177
	s_cmp_ge_i32 s61, 2
	s_cbranch_scc1 .Lamoba_sm0
	v_subrev_u32_e32 v184, 32, v179
	v_cmp_le_i32_e32 vcc, 0, v179
	s_nop 1
	v_cndmask_b32_e32 v32, v199, v32, vcc
	v_cmp_le_i32_e32 vcc, 1, v179
	s_nop 1
	v_cndmask_b32_e32 v33, v199, v33, vcc
	v_cmp_le_i32_e32 vcc, 2, v179
	s_nop 1
	v_cndmask_b32_e32 v34, v199, v34, vcc
	v_cmp_le_i32_e32 vcc, 3, v179
	s_nop 1
	v_cndmask_b32_e32 v35, v199, v35, vcc
	v_cmp_le_i32_e32 vcc, 8, v179
	s_nop 1
	v_cndmask_b32_e32 v36, v199, v36, vcc
	v_cmp_le_i32_e32 vcc, 9, v179
	s_nop 1
	v_cndmask_b32_e32 v37, v199, v37, vcc
	v_cmp_le_i32_e32 vcc, 10, v179
	s_nop 1
	v_cndmask_b32_e32 v38, v199, v38, vcc
	v_cmp_le_i32_e32 vcc, 11, v179
	s_nop 1
	v_cndmask_b32_e32 v39, v199, v39, vcc
	v_cmp_le_i32_e32 vcc, 16, v179
	s_nop 1
	v_cndmask_b32_e32 v40, v199, v40, vcc
	v_cmp_le_i32_e32 vcc, 17, v179
	s_nop 1
	v_cndmask_b32_e32 v41, v199, v41, vcc
	v_cmp_le_i32_e32 vcc, 18, v179
	s_nop 1
	v_cndmask_b32_e32 v42, v199, v42, vcc
	v_cmp_le_i32_e32 vcc, 19, v179
	s_nop 1
	v_cndmask_b32_e32 v43, v199, v43, vcc
	v_cmp_le_i32_e32 vcc, 24, v179
	s_nop 1
	v_cndmask_b32_e32 v44, v199, v44, vcc
	v_cmp_le_i32_e32 vcc, 25, v179
	s_nop 1
	v_cndmask_b32_e32 v45, v199, v45, vcc
	v_cmp_le_i32_e32 vcc, 26, v179
	s_nop 1
	v_cndmask_b32_e32 v46, v199, v46, vcc
	v_cmp_le_i32_e32 vcc, 27, v179
	s_nop 1
	v_cndmask_b32_e32 v47, v199, v47, vcc
	v_cmp_le_i32_e32 vcc, 0, v184
	s_nop 1
	v_cndmask_b32_e32 v48, v199, v48, vcc
	v_cmp_le_i32_e32 vcc, 1, v184
	s_nop 1
	v_cndmask_b32_e32 v49, v199, v49, vcc
	v_cmp_le_i32_e32 vcc, 2, v184
	s_nop 1
	v_cndmask_b32_e32 v50, v199, v50, vcc
	v_cmp_le_i32_e32 vcc, 3, v184
	s_nop 1
	v_cndmask_b32_e32 v51, v199, v51, vcc
	v_cmp_le_i32_e32 vcc, 8, v184
	s_nop 1
	v_cndmask_b32_e32 v52, v199, v52, vcc
	v_cmp_le_i32_e32 vcc, 9, v184
	s_nop 1
	v_cndmask_b32_e32 v53, v199, v53, vcc
	v_cmp_le_i32_e32 vcc, 10, v184
	s_nop 1
	v_cndmask_b32_e32 v54, v199, v54, vcc
	v_cmp_le_i32_e32 vcc, 11, v184
	s_nop 1
	v_cndmask_b32_e32 v55, v199, v55, vcc
	v_cmp_le_i32_e32 vcc, 16, v184
	s_nop 1
	v_cndmask_b32_e32 v56, v199, v56, vcc
	v_cmp_le_i32_e32 vcc, 17, v184
	s_nop 1
	v_cndmask_b32_e32 v57, v199, v57, vcc
	v_cmp_le_i32_e32 vcc, 18, v184
	s_nop 1
	v_cndmask_b32_e32 v58, v199, v58, vcc
	v_cmp_le_i32_e32 vcc, 19, v184
	s_nop 1
	v_cndmask_b32_e32 v59, v199, v59, vcc
	v_cmp_le_i32_e32 vcc, 24, v184
	s_nop 1
	v_cndmask_b32_e32 v60, v199, v60, vcc
	v_cmp_le_i32_e32 vcc, 25, v184
	s_nop 1
	v_cndmask_b32_e32 v61, v199, v61, vcc
	v_cmp_le_i32_e32 vcc, 26, v184
	s_nop 1
	v_cndmask_b32_e32 v62, v199, v62, vcc
	v_cmp_le_i32_e32 vcc, 27, v184
	s_nop 1
	v_cndmask_b32_e32 v63, v199, v63, vcc
